# attention masked path: compares issued three at a time into s[98:99]/s[100:101]/vcc then their selects, removing 116 s_nop 1 (8 blocks), on top of v41
# speedup vs baseline: 1.0008x; 1.0008x over previous
; #define LAS __attribute__((address_space(3)))
; __device__ __forceinline__ void load_frags(KVFrag& f, const bf16_t* K0, const bf16_t* V0, int kb, int mode, int rsel, int lane) {
;     ...
;     } else {
;         const int k0 = lane >> 3;
;         const int eo = (k0 * 256 + (kb >> 4)) * 64 + (lane & 7) * 8;
;         const bf16_t* kp = K0 + eo; const bf16_t* vp = V0 + eo;
; #pragma unroll
;         for (int i = 0; i < 4; ++i) { const int o = (i & 1) * (8 * 256 * 64) + (i >> 1) * 64; f.kr[i] = *(const bf16x8*)(kp + o); f.vr[i] = *(const bf16x8*)(vp + o); }
;     }
; }
; __device__ __forceinline__ void stage_v(const KVFrag& f, LAS unsigned char* vst, int lane, int hi, bf16x8 (&vf)[2][2], bf16x8 (&kf)[4]) {
; #pragma unroll
;     for (int i = 0; i < 4; ++i) { const int c = lane + 64 * i; *(LAS bf16x8*)(vst + (c >> 3) * VST_RS + (c & 7) * 16) = f.vr[i]; *(LAS bf16x8*)(vst + KST_OFF + (c >> 3) * KST_RS + (c & 7) * 16) = f.kr[i]; }
;     const LAS unsigned char* tb = vst + (8 * hi + ((lane & 15) >> 2)) * VST_RS + (16 * ((lane >> 4) & 1) + 4 * (lane & 3)) * 2;
; #pragma unroll
;     for (int ks = 0; ks < 2; ++ks)
; #pragma unroll
;         for (int dh = 0; dh < 2; ++dh) {
;             const s16x4 lo = __builtin_bit_cast(s16x4, __builtin_amdgcn_ds_read_tr16_b64_v4i16((LAS s16x4*)(tb + (16 * ks) * VST_RS + dh * 64)));
;             const s16x4 hi4 = __builtin_bit_cast(s16x4, __builtin_amdgcn_ds_read_tr16_b64_v4i16((LAS s16x4*)(tb + (16 * ks + 4) * VST_RS + dh * 64)));
;             vf[ks][dh] = (bf16x8){lo[0], lo[1], lo[2], lo[3], hi4[0], hi4[1], hi4[2], hi4[3]};
;         }
;     const int l31 = lane & 31, jsw = (l31 & 0x13) | ((l31 & 4) << 1) | ((l31 & 8) >> 1);
;     const LAS unsigned char* kb_ = vst + KST_OFF + jsw * KST_RS + 16 * hi;
; #pragma unroll
;     for (int d0 = 0; d0 < 4; ++d0) kf[d0] = *(const LAS bf16x8*)(kb_ + 32 * d0);
; }
; __device__ __forceinline__ unsigned orow_off(const ORows& R, int rr) { return (R.base_row + R.pstride * ((unsigned)rr & R.amask)) * R.ld + R.hcol + 64u * ((unsigned)rr >> R.ashift); }
; __device__ __forceinline__ void qk_tile(const bf16x8 (&kf)[4], const LAS unsigned char* qh, f32x16& s) {
;     const f32x16 z = {0.f, 0.f, 0.f, 0.f, 0.f, 0.f, 0.f, 0.f, 0.f, 0.f, 0.f, 0.f, 0.f, 0.f, 0.f, 0.f};
;     s = __builtin_amdgcn_mfma_f32_32x32x16_bf16(kf[0], *(const LAS bf16x8*)qh, z, 0, 0, 0);
; #pragma unroll
.LBB0_422:
	s_add_i32 s28, s13, s12
	s_sub_i32 s38, s28, 64
	s_sub_i32 s39, s28, 32
	s_lshr_b32 s28, s39, 4
	v_add_u32_e32 v0, s28, v198
	v_lshl_or_b32 v2, v0, 6, v192
	v_ashrrev_i32_e32 v3, 31, v2
	v_lshlrev_b64 v[2:3], 1, v[2:3]
	v_lshl_add_u64 v[6:7], s[20:21], 0, v[2:3]
	v_add_co_u32_e32 v14, vcc, s96, v6
	v_lshl_add_u64 v[10:11], s[22:23], 0, v[2:3]
	s_nop 0
	v_addc_co_u32_e32 v15, vcc, 0, v7, vcc
	v_add_co_u32_e32 v104, vcc, s96, v10
	global_load_dwordx4 v[2:5], v[6:7], off
	s_nop 0
	global_load_dwordx4 v[6:9], v[6:7], off offset:128
	v_addc_co_u32_e32 v105, vcc, 0, v11, vcc
	s_waitcnt vmcnt(7)
	ds_write_b128 v212, v[116:119] offset:9216
	ds_write_b128 v193, v[112:115] offset:15360
	s_waitcnt vmcnt(3)
	ds_write_b128 v213, v[136:139] offset:9216
	ds_write_b128 v194, v[120:123] offset:15360
	s_waitcnt vmcnt(4)
	ds_write_b128 v214, v[128:131] offset:9216
	ds_write_b128 v195, v[124:127] offset:15360
	s_waitcnt vmcnt(2)
	ds_write_b128 v215, v[140:143] offset:9216
	ds_write_b128 v196, v[132:135] offset:15360
	v_add_u32_e32 v0, v182, v191
	ds_read_b128 v[96:99], v217 offset:15360
	global_load_dwordx4 v[112:115], v[10:11], off
	s_nop 0
	global_load_dwordx4 v[10:13], v[10:11], off offset:128
	ds_read_b128 v[80:83], v0
	global_load_dwordx4 v[120:123], v[14:15], off
	global_load_dwordx4 v[116:119], v[14:15], off offset:128
	ds_read_b128 v[148:151], v217 offset:15392
	ds_read_b128 v[100:103], v0 offset:32
	global_load_dwordx4 v[128:131], v[104:105], off
	global_load_dwordx4 v[124:127], v[104:105], off offset:128
	s_waitcnt lgkmcnt(2)
	v_mfma_f32_32x32x16_bf16 v[80:95], v[96:99], v[80:83], 0
	s_cmp_ge_i32 s38, s15
	s_cselect_b64 s[28:29], -1, 0
	s_cmp_le_i32 s38, s16
	s_cselect_b64 s[36:37], -1, 0
	s_and_b64 s[28:29], s[28:29], s[36:37]
	v_add_u32_e32 v14, s12, v211
	s_and_b64 vcc, exec, s[28:29]
	s_waitcnt lgkmcnt(0)
	v_mfma_f32_32x32x16_bf16 v[80:95], v[148:151], v[100:103], v[80:95]
	ds_read_b128 v[156:159], v217 offset:15424
	ds_read_b128 v[100:103], v0 offset:64
	ds_read_b128 v[152:155], v217 offset:15456
	ds_read_b128 v[104:107], v0 offset:96
	ds_read_b64_tr_b16 v[132:133], v216 offset:9216
	ds_read_b64_tr_b16 v[134:135], v216 offset:9984
	ds_read_b64_tr_b16 v[138:139], v216 offset:10048
	ds_read_b64_tr_b16 v[136:137], v216 offset:9280
	ds_read_b64_tr_b16 v[140:141], v216 offset:12288
	ds_read_b64_tr_b16 v[142:143], v216 offset:13056
	ds_read_b64_tr_b16 v[146:147], v216 offset:13120
	ds_read_b64_tr_b16 v[144:145], v216 offset:12352
	v_cmp_gt_u32_e64 s[36:37], s94, v14
	v_add_u32_e32 v219, 0xffffff80, v14
	v_add_u32_e32 v218, 0xffffff81, v14
	v_add_u32_e32 v204, 0xffffff82, v14
	v_add_u32_e32 v203, 0xffffff83, v14
	s_waitcnt lgkmcnt(10)
	v_mfma_f32_32x32x16_bf16 v[80:95], v[156:159], v[100:103], v[80:95]
	v_add_u32_e32 v201, 0xffffff84, v14
	v_add_u32_e32 v200, 0xffffff85, v14
	v_add_u32_e32 v167, 0xffffff86, v14
	v_add_u32_e32 v166, 0xffffff8f, v14
	v_add_u32_e32 v165, 0xffffff90, v14
	v_add_u32_e32 v164, 0xffffff91, v14
	v_add_u32_e32 v163, 0xffffff92, v14
	s_waitcnt lgkmcnt(8)
	v_mfma_f32_32x32x16_bf16 v[80:95], v[152:155], v[104:107], v[80:95]
	v_add_u32_e32 v162, 0xffffff93, v14
	v_add_u32_e32 v161, 0xffffff94, v14
	v_add_u32_e32 v160, 0xffffff95, v14
	v_add_u32_e32 v15, 0xffffff96, v14
	s_cbranch_vccnz .LBB0_424
	v_cmp_lt_u32_e32 vcc, s59, v219
	s_nop 5
	v_cndmask_b32_e64 v80, v202, v80, s[36:37]
	v_cndmask_b32_e32 v81, v202, v81, vcc
	v_cmp_lt_u32_e64 s[98:99], s59, v218
	v_cmp_lt_u32_e64 s[100:101], s59, v204
	v_cmp_lt_u32_e32 vcc, s59, v203
	v_cndmask_b32_e64 v82, v202, v82, s[98:99]
	v_cndmask_b32_e64 v83, v202, v83, s[100:101]
	v_cndmask_b32_e32 v84, v202, v84, vcc
	v_cmp_lt_u32_e64 s[98:99], s59, v201
	v_cmp_lt_u32_e64 s[100:101], s59, v200
	v_cmp_lt_u32_e32 vcc, s59, v167
	v_cndmask_b32_e64 v85, v202, v85, s[98:99]
	v_cndmask_b32_e64 v86, v202, v86, s[100:101]
	v_cndmask_b32_e32 v87, v202, v87, vcc
	v_cmp_lt_u32_e64 s[98:99], s59, v166
	v_cmp_lt_u32_e64 s[100:101], s59, v165
	v_cmp_lt_u32_e32 vcc, s59, v164
	v_cndmask_b32_e64 v88, v202, v88, s[98:99]
	v_cndmask_b32_e64 v89, v202, v89, s[100:101]
	v_cndmask_b32_e32 v90, v202, v90, vcc
	v_cmp_lt_u32_e64 s[98:99], s59, v163
	v_cmp_lt_u32_e64 s[100:101], s59, v162
	v_cmp_lt_u32_e32 vcc, s59, v161
	v_cndmask_b32_e64 v91, v202, v91, s[98:99]
	v_cndmask_b32_e64 v92, v202, v92, s[100:101]
	v_cndmask_b32_e32 v93, v202, v93, vcc
	v_cmp_lt_u32_e64 s[98:99], s59, v160
	v_cmp_lt_u32_e32 vcc, s59, v15
	s_nop 0
	v_cndmask_b32_e64 v94, v202, v94, s[98:99]
	v_cndmask_b32_e32 v95, v202, v95, vcc

; #define LAS __attribute__((address_space(3)))
; __device__ __forceinline__ void qk_tile(const bf16x8 (&kf)[4], const LAS unsigned char* qh, f32x16& s) {
;     const f32x16 z = {0.f, 0.f, 0.f, 0.f, 0.f, 0.f, 0.f, 0.f, 0.f, 0.f, 0.f, 0.f, 0.f, 0.f, 0.f, 0.f};
;     s = __builtin_amdgcn_mfma_f32_32x32x16_bf16(kf[0], *(const LAS bf16x8*)qh, z, 0, 0, 0);
; #pragma unroll
;     for (int d0 = 1; d0 < 4; ++d0) s = __builtin_amdgcn_mfma_f32_32x32x16_bf16(kf[d0], *(const LAS bf16x8*)(qh + 32 * d0), s, 0, 0, 0);
; }
; __device__ __forceinline__ void softmax_head(f32x16& s, int kb, int lq, int radius, bool full, int hi, HState& S) {
;     if (!full) {
; #pragma unroll
;         for (int r = 0; r < 16; ++r) { const int lk = kb + 16 * (r >> 3) + 8 * hi + (r & 7); const int d = lk - lq;
;             const bool valid = (unsigned)(d + radius) <= (unsigned)(2 * radius); s[r] = valid ? s[r] : -INFINITY; }
;     }
.LBB0_426:
	s_xor_b64 s[28:29], s[28:29], -1
	ds_read_b128 v[100:103], v0 offset:4608
	ds_read_b128 v[220:223], v0 offset:4640
	s_waitcnt lgkmcnt(1)
	v_mfma_f32_32x32x16_bf16 v[96:111], v[96:99], v[100:103], 0
	s_waitcnt lgkmcnt(0)
	v_mfma_f32_32x32x16_bf16 v[96:111], v[148:151], v[220:223], v[96:111]
	ds_read_b128 v[148:151], v0 offset:4672
	s_waitcnt lgkmcnt(0)
	v_mfma_f32_32x32x16_bf16 v[96:111], v[156:159], v[148:151], v[96:111]
	ds_read_b128 v[148:151], v0 offset:4704
	s_waitcnt lgkmcnt(0)
	v_mfma_f32_32x32x16_bf16 v[96:111], v[152:155], v[148:151], v[96:111]
	s_andn2_b64 vcc, exec, s[28:29]
	s_cbranch_vccnz .LBB0_428
	v_cmp_gt_u32_e32 vcc, s94, v14
	s_nop 8
	v_cndmask_b32_e32 v96, v202, v96, vcc
	v_cmp_lt_u32_e64 s[98:99], s59, v219
	v_cmp_lt_u32_e64 s[100:101], s59, v218
	v_cmp_lt_u32_e32 vcc, s59, v204
	v_cndmask_b32_e64 v97, v202, v97, s[98:99]
	v_cndmask_b32_e64 v98, v202, v98, s[100:101]
	v_cndmask_b32_e32 v99, v202, v99, vcc
	v_cmp_lt_u32_e64 s[98:99], s59, v203
	v_cmp_lt_u32_e64 s[100:101], s59, v201
	v_cmp_lt_u32_e32 vcc, s59, v200
	v_cndmask_b32_e64 v100, v202, v100, s[98:99]
	v_cndmask_b32_e64 v101, v202, v101, s[100:101]
	v_cndmask_b32_e32 v102, v202, v102, vcc
	v_cmp_lt_u32_e64 s[98:99], s59, v167
	v_cmp_lt_u32_e64 s[100:101], s59, v166
	v_cmp_lt_u32_e32 vcc, s59, v165
	v_cndmask_b32_e64 v103, v202, v103, s[98:99]
	v_cndmask_b32_e64 v104, v202, v104, s[100:101]
	v_cndmask_b32_e32 v105, v202, v105, vcc
	v_cmp_lt_u32_e64 s[98:99], s59, v164
	v_cmp_lt_u32_e64 s[100:101], s59, v163
	v_cmp_lt_u32_e32 vcc, s59, v162
	v_cndmask_b32_e64 v106, v202, v106, s[98:99]
	v_cndmask_b32_e64 v107, v202, v107, s[100:101]
	v_cndmask_b32_e32 v108, v202, v108, vcc
	v_cmp_lt_u32_e64 s[98:99], s59, v161
	v_cmp_lt_u32_e64 s[100:101], s59, v160
	v_cmp_lt_u32_e32 vcc, s59, v15
	v_cndmask_b32_e64 v109, v202, v109, s[98:99]
	v_cndmask_b32_e64 v110, v202, v110, s[100:101]
	v_cndmask_b32_e32 v111, v202, v111, vcc

; #define LAS __attribute__((address_space(3)))
; __device__ __forceinline__ void load_frags(KVFrag& f, const bf16_t* K0, const bf16_t* V0, int kb, int mode, int rsel, int lane) {
;     ...
;     } else {
;         const int k0 = lane >> 3;
;         const int eo = (k0 * 256 + (kb >> 4)) * 64 + (lane & 7) * 8;
;         const bf16_t* kp = K0 + eo; const bf16_t* vp = V0 + eo;
; #pragma unroll
;         for (int i = 0; i < 4; ++i) { const int o = (i & 1) * (8 * 256 * 64) + (i >> 1) * 64; f.kr[i] = *(const bf16x8*)(kp + o); f.vr[i] = *(const bf16x8*)(vp + o); }
;     }
; }
; __device__ __forceinline__ void stage_v(const KVFrag& f, LAS unsigned char* vst, int lane, int hi, bf16x8 (&vf)[2][2], bf16x8 (&kf)[4]) {
; #pragma unroll
;     for (int i = 0; i < 4; ++i) { const int c = lane + 64 * i; *(LAS bf16x8*)(vst + (c >> 3) * VST_RS + (c & 7) * 16) = f.vr[i]; *(LAS bf16x8*)(vst + KST_OFF + (c >> 3) * KST_RS + (c & 7) * 16) = f.kr[i]; }
;     const LAS unsigned char* tb = vst + (8 * hi + ((lane & 15) >> 2)) * VST_RS + (16 * ((lane >> 4) & 1) + 4 * (lane & 3)) * 2;
; #pragma unroll
;     for (int ks = 0; ks < 2; ++ks)
; #pragma unroll
;         for (int dh = 0; dh < 2; ++dh) {
; __device__ __forceinline__ void softmax_tail(f32x16& s, HState& S, u32x4 (&pw)[2]) {
;     const float mn = S.m;
; #pragma unroll
;     for (int r = 0; r < 16; ++r) s[r] -= mn;
; #pragma unroll
;     for (int r = 0; r < 16; ++r) s[r] = __builtin_amdgcn_exp2f(s[r]);
;     float p0 = s[0], p1 = s[1];
; #pragma unroll
;     for (int r = 2; r < 16; r += 2) { p0 += s[r]; p1 += s[r + 1]; }
;     S.l += p0 + p1;
; #pragma unroll
;     for (int ks = 0; ks < 2; ++ks) { pw[ks].x = cvtpk_s(s[8 * ks + 0], s[8 * ks + 1]); pw[ks].y = cvtpk_s(s[8 * ks + 2], s[8 * ks + 3]); pw[ks].z = cvtpk_s(s[8 * ks + 4], s[8 * ks + 5]); pw[ks].w = cvtpk_s(s[8 * ks + 6], s[8 * ks + 7]); }
; }
; __device__ __forceinline__ void softmax_tile(f32x16& s, int kb, int lq, int radius, bool full, int hi, HState& S, u32x4 (&pw)[2]) { softmax_head(s, kb, lq, radius, full, hi, S); softmax_tail(s, S, pw); }
; __device__ __forceinline__ void pv_tile(const bf16x8 (&vf)[2][2], const u32x4 (&pw)[2], HState& S) {
; #pragma unroll
;     for (int ks = 0; ks < 2; ++ks)
; #pragma unroll
;         for (int dh = 0; dh < 2; ++dh) S.o[dh] = __builtin_amdgcn_mfma_f32_32x32x16_bf16(vf[ks][dh], __builtin_bit_cast(bf16x8, pw[ks]), S.o[dh], 0, 0, 0);
.LBB0_430:
	v_sub_f32_e32 v15, v80, v184
	v_sub_f32_e32 v80, v81, v184
	v_sub_f32_e32 v81, v82, v184
	v_sub_f32_e32 v82, v83, v184
	v_sub_f32_e32 v83, v84, v184
	v_sub_f32_e32 v84, v85, v184
	v_sub_f32_e32 v85, v86, v184
	v_sub_f32_e32 v86, v87, v184
	v_sub_f32_e32 v87, v88, v184
	v_sub_f32_e32 v88, v89, v184
	v_sub_f32_e32 v89, v90, v184
	v_sub_f32_e32 v90, v91, v184
	v_sub_f32_e32 v91, v92, v184
	v_sub_f32_e32 v92, v93, v184
	v_sub_f32_e32 v93, v94, v184
	v_sub_f32_e32 v94, v95, v184
	v_exp_f32_e32 v233, v15
	v_exp_f32_e32 v234, v80
	v_exp_f32_e32 v235, v81
	v_exp_f32_e32 v236, v82
	v_exp_f32_e32 v237, v83
	v_exp_f32_e32 v238, v84
	v_exp_f32_e32 v239, v85
	v_exp_f32_e32 v240, v86
	v_exp_f32_e32 v241, v87
	v_exp_f32_e32 v242, v88
	v_exp_f32_e32 v243, v89
	v_exp_f32_e32 v244, v90
	v_exp_f32_e32 v245, v91
	v_exp_f32_e32 v246, v92
	v_exp_f32_e32 v247, v93
	v_exp_f32_e32 v248, v94
	v_cvt_pk_bf16_f32 v80, v241, v242
	v_cvt_pk_bf16_f32 v81, v243, v244
	v_cvt_pk_bf16_f32 v82, v245, v246
	v_cvt_pk_bf16_f32 v83, v247, v248
	v_cvt_pk_bf16_f32 v84, v233, v234
	v_cvt_pk_bf16_f32 v85, v235, v236
	v_cvt_pk_bf16_f32 v86, v237, v238
	v_cvt_pk_bf16_f32 v87, v239, v240
	s_nop 1
	v_mfma_f32_32x32x16_bf16 v[64:79], v[132:135], v[84:87], v[64:79]
	v_sub_f32_e32 v15, v96, v183
	v_sub_f32_e32 v88, v105, v183
	v_sub_f32_e32 v89, v106, v183
	v_sub_f32_e32 v90, v107, v183
	v_sub_f32_e32 v91, v108, v183
	v_sub_f32_e32 v92, v109, v183
	v_sub_f32_e32 v93, v110, v183
	v_sub_f32_e32 v94, v111, v183
	v_mfma_f32_32x32x16_bf16 v[48:63], v[136:139], v[84:87], v[48:63]
	v_sub_f32_e32 v84, v101, v183
	v_sub_f32_e32 v85, v102, v183
	v_sub_f32_e32 v86, v103, v183
	v_sub_f32_e32 v87, v104, v183
	v_exp_f32_e32 v15, v15
	v_exp_f32_e32 v222, v84
	v_exp_f32_e32 v223, v85
	v_mfma_f32_32x32x16_bf16 v[64:79], v[140:143], v[80:83], v[64:79]
	v_exp_f32_e32 v224, v86
	v_exp_f32_e32 v225, v87
	v_exp_f32_e32 v226, v88
	v_exp_f32_e32 v227, v89
	v_exp_f32_e32 v228, v90
	v_exp_f32_e32 v229, v91
	v_exp_f32_e32 v230, v92
	v_mfma_f32_32x32x16_bf16 v[48:63], v[144:147], v[80:83], v[48:63]
	v_sub_f32_e32 v80, v97, v183
	v_sub_f32_e32 v81, v98, v183
	v_sub_f32_e32 v82, v99, v183
	v_sub_f32_e32 v83, v100, v183
	v_exp_f32_e32 v218, v80
	v_exp_f32_e32 v219, v81
	v_exp_f32_e32 v220, v82
	v_exp_f32_e32 v221, v83
	v_exp_f32_e32 v231, v93
	v_exp_f32_e32 v232, v94
	v_cvt_pk_bf16_f32 v80, v225, v226
	v_cvt_pk_bf16_f32 v81, v227, v228
	v_cvt_pk_bf16_f32 v82, v229, v230
	v_cvt_pk_bf16_f32 v83, v231, v232
	v_cvt_pk_bf16_f32 v84, v15, v218
	v_cvt_pk_bf16_f32 v85, v219, v220
	v_cvt_pk_bf16_f32 v86, v221, v222
	v_cvt_pk_bf16_f32 v87, v223, v224
	s_nop 1
	v_mfma_f32_32x32x16_bf16 v[32:47], v[132:135], v[84:87], v[32:47]
	v_mfma_f32_32x32x16_bf16 v[16:31], v[136:139], v[84:87], v[16:31]
	v_mfma_f32_32x32x16_bf16 v[32:47], v[140:143], v[80:83], v[32:47]
	v_mfma_f32_32x32x16_bf16 v[16:31], v[144:147], v[80:83], v[16:31]
	s_add_i32 s36, s11, 2
	s_min_i32 s28, s36, s14
	s_lshl_b32 s28, s28, 5
	s_add_i32 s28, s28, s9
	s_lshr_b32 s28, s28, 4
	v_add_u32_e32 v80, s28, v198
	v_lshl_or_b32 v80, v80, 6, v192
	v_ashrrev_i32_e32 v81, 31, v80
	v_lshlrev_b64 v[80:81], 1, v[80:81]
	v_lshl_add_u64 v[82:83], s[20:21], 0, v[80:81]
	v_add_co_u32_e32 v84, vcc, s96, v82
	v_lshl_add_u64 v[80:81], s[22:23], 0, v[80:81]
	s_nop 0
	v_addc_co_u32_e32 v85, vcc, 0, v83, vcc
	v_add_co_u32_e32 v100, vcc, s96, v80
	s_waitcnt vmcnt(5)
	ds_write_b128 v212, v[112:115] offset:9216
	v_addc_co_u32_e32 v101, vcc, 0, v81, vcc
	ds_write_b128 v193, v[2:5] offset:15360
	s_waitcnt vmcnt(1)
	ds_write_b128 v213, v[128:131] offset:9216
	ds_write_b128 v194, v[120:123] offset:15360
	ds_write_b128 v214, v[10:13] offset:9216
	ds_write_b128 v195, v[6:9] offset:15360
	s_waitcnt vmcnt(0)
	ds_write_b128 v215, v[124:127] offset:9216
	ds_write_b128 v196, v[116:119] offset:15360
	global_load_dwordx4 v[112:115], v[82:83], off
	global_load_dwordx4 v[124:127], v[82:83], off offset:128
	global_load_dwordx4 v[116:119], v[80:81], off
	global_load_dwordx4 v[128:131], v[80:81], off offset:128
	global_load_dwordx4 v[120:123], v[84:85], off
	global_load_dwordx4 v[132:135], v[84:85], off offset:128
	global_load_dwordx4 v[136:139], v[100:101], off
	global_load_dwordx4 v[140:143], v[100:101], off offset:128
	ds_read_b128 v[96:99], v217 offset:15360
	ds_read_b128 v[2:5], v0
	ds_read_b128 v[148:151], v217 offset:15392
	s_waitcnt lgkmcnt(1)
	v_mfma_f32_32x32x16_bf16 v[80:95], v[96:99], v[2:5], 0
	ds_read_b128 v[6:9], v0 offset:32
	ds_read_b128 v[156:159], v217 offset:15424
	ds_read_b128 v[2:5], v0 offset:64
	ds_read_b128 v[152:155], v217 offset:15456
	ds_read_b128 v[100:103], v0 offset:96
	ds_read_b64_tr_b16 v[12:13], v216 offset:10048
	ds_read_b64_tr_b16 v[10:11], v216 offset:9280
	s_waitcnt lgkmcnt(6)
	v_mfma_f32_32x32x16_bf16 v[80:95], v[148:151], v[6:9], v[80:95]
	ds_read_b64_tr_b16 v[6:7], v216 offset:9216
	ds_read_b64_tr_b16 v[8:9], v216 offset:9984
	ds_read_b64_tr_b16 v[144:145], v216 offset:12288
	ds_read_b64_tr_b16 v[146:147], v216 offset:13056
	s_cmp_ge_i32 s39, s15
	s_cselect_b64 s[28:29], -1, 0
	s_cmp_le_i32 s38, s17
	s_waitcnt lgkmcnt(8)
	v_mfma_f32_32x32x16_bf16 v[80:95], v[156:159], v[2:5], v[80:95]
	ds_read_b64_tr_b16 v[4:5], v216 offset:13120
	ds_read_b64_tr_b16 v[2:3], v216 offset:12352
	s_cselect_b64 s[38:39], -1, 0
	s_and_b64 s[28:29], s[28:29], s[38:39]
	s_and_b64 vcc, exec, s[28:29]
	v_add_u32_e32 v200, 32, v14
	v_add_u32_e32 v163, 0xffffffa0, v14
	s_waitcnt lgkmcnt(8)
	v_mfma_f32_32x32x16_bf16 v[80:95], v[152:155], v[100:103], v[80:95]
	v_add_u32_e32 v162, 0xffffffa1, v14
	v_add_u32_e32 v161, 0xffffffa2, v14
	v_add_u32_e32 v160, 0xffffffa3, v14
	v_add_u32_e32 v167, 0xffffffa4, v14
	v_add_u32_e32 v166, 0xffffffa5, v14
	v_add_u32_e32 v165, 0xffffffa6, v14
	v_add_u32_e32 v164, 0xffffffaf, v14
	v_add_u32_e32 v204, 0xffffffb0, v14
	v_add_u32_e32 v252, 0xffffffb1, v14
	v_add_u32_e32 v251, 0xffffffb2, v14
	v_add_u32_e32 v250, 0xffffffb3, v14
	v_add_u32_e32 v249, 0xffffffb4, v14
	v_add_u32_e32 v203, 0xffffffb5, v14
	v_add_u32_e32 v201, 0xffffffb6, v14
	s_cbranch_vccnz .LBB0_432
; __device__ __forceinline__ void softmax_head(f32x16& s, int kb, int lq, int radius, bool full, int hi, HState& S) {
;     if (!full) {
; #pragma unroll
;         for (int r = 0; r < 16; ++r) { const int lk = kb + 16 * (r >> 3) + 8 * hi + (r & 7); const int d = lk - lq;
;             const bool valid = (unsigned)(d + radius) <= (unsigned)(2 * radius); s[r] = valid ? s[r] : -INFINITY; }
;     }
	v_cmp_gt_u32_e32 vcc, s94, v200
	s_nop 1
	v_cndmask_b32_e32 v80, v202, v80, vcc
	v_cmp_lt_u32_e64 s[98:99], s59, v163
	v_cmp_lt_u32_e64 s[100:101], s59, v162
	v_cmp_lt_u32_e32 vcc, s59, v161
	v_cndmask_b32_e64 v81, v202, v81, s[98:99]
	v_cndmask_b32_e64 v82, v202, v82, s[100:101]
	v_cndmask_b32_e32 v83, v202, v83, vcc
	v_cmp_lt_u32_e64 s[98:99], s59, v160
	v_cmp_lt_u32_e64 s[100:101], s59, v167
	v_cmp_lt_u32_e32 vcc, s59, v166
	v_cndmask_b32_e64 v84, v202, v84, s[98:99]
	v_cndmask_b32_e64 v85, v202, v85, s[100:101]
	v_cndmask_b32_e32 v86, v202, v86, vcc
	v_cmp_lt_u32_e64 s[98:99], s59, v165
	v_cmp_lt_u32_e64 s[100:101], s59, v164
	v_cmp_lt_u32_e32 vcc, s59, v204
	v_cndmask_b32_e64 v87, v202, v87, s[98:99]
	v_cndmask_b32_e64 v88, v202, v88, s[100:101]
	v_cndmask_b32_e32 v89, v202, v89, vcc
	v_cmp_lt_u32_e64 s[98:99], s59, v252
	v_cmp_lt_u32_e64 s[100:101], s59, v251
	v_cmp_lt_u32_e32 vcc, s59, v250
	v_cndmask_b32_e64 v90, v202, v90, s[98:99]
	v_cndmask_b32_e64 v91, v202, v91, s[100:101]
	v_cndmask_b32_e32 v92, v202, v92, vcc
	v_cmp_lt_u32_e64 s[98:99], s59, v249
	v_cmp_lt_u32_e64 s[100:101], s59, v203
	v_cmp_lt_u32_e32 vcc, s59, v201
	v_cndmask_b32_e64 v93, v202, v93, s[98:99]
	v_cndmask_b32_e64 v94, v202, v94, s[100:101]
	v_cndmask_b32_e32 v95, v202, v95, vcc

; #define LAS __attribute__((address_space(3)))
; __device__ __forceinline__ void qk_tile(const bf16x8 (&kf)[4], const LAS unsigned char* qh, f32x16& s) {
;     const f32x16 z = {0.f, 0.f, 0.f, 0.f, 0.f, 0.f, 0.f, 0.f, 0.f, 0.f, 0.f, 0.f, 0.f, 0.f, 0.f, 0.f};
;     s = __builtin_amdgcn_mfma_f32_32x32x16_bf16(kf[0], *(const LAS bf16x8*)qh, z, 0, 0, 0);
; #pragma unroll
;     for (int d0 = 1; d0 < 4; ++d0) s = __builtin_amdgcn_mfma_f32_32x32x16_bf16(kf[d0], *(const LAS bf16x8*)(qh + 32 * d0), s, 0, 0, 0);
; }
; __device__ __forceinline__ void softmax_head(f32x16& s, int kb, int lq, int radius, bool full, int hi, HState& S) {
;     if (!full) {
; #pragma unroll
;         for (int r = 0; r < 16; ++r) { const int lk = kb + 16 * (r >> 3) + 8 * hi + (r & 7); const int d = lk - lq;
;             const bool valid = (unsigned)(d + radius) <= (unsigned)(2 * radius); s[r] = valid ? s[r] : -INFINITY; }
;     }
.LBB0_434:
	s_xor_b64 s[28:29], s[28:29], -1
	ds_read_b128 v[100:103], v0 offset:4608
	ds_read_b128 v[234:237], v0 offset:4640
	s_waitcnt lgkmcnt(1)
	v_mfma_f32_32x32x16_bf16 v[96:111], v[96:99], v[100:103], 0
	s_waitcnt lgkmcnt(0)
	v_mfma_f32_32x32x16_bf16 v[96:111], v[148:151], v[234:237], v[96:111]
	ds_read_b128 v[148:151], v0 offset:4672
	s_waitcnt lgkmcnt(0)
	v_mfma_f32_32x32x16_bf16 v[96:111], v[156:159], v[148:151], v[96:111]
	ds_read_b128 v[148:151], v0 offset:4704
	s_waitcnt lgkmcnt(0)
	v_mfma_f32_32x32x16_bf16 v[96:111], v[152:155], v[148:151], v[96:111]
	s_andn2_b64 vcc, exec, s[28:29]
	s_cbranch_vccnz .LBB0_436
	v_cmp_gt_u32_e32 vcc, s94, v200
	s_nop 8
	v_cndmask_b32_e32 v96, v202, v96, vcc
	v_cmp_lt_u32_e64 s[98:99], s59, v163
	v_cmp_lt_u32_e64 s[100:101], s59, v162
	v_cmp_lt_u32_e32 vcc, s59, v161
	v_cndmask_b32_e64 v97, v202, v97, s[98:99]
	v_cndmask_b32_e64 v98, v202, v98, s[100:101]
	v_cndmask_b32_e32 v99, v202, v99, vcc
	v_cmp_lt_u32_e64 s[98:99], s59, v160
	v_cmp_lt_u32_e64 s[100:101], s59, v167
	v_cmp_lt_u32_e32 vcc, s59, v166
	v_cndmask_b32_e64 v100, v202, v100, s[98:99]
	v_cndmask_b32_e64 v101, v202, v101, s[100:101]
	v_cndmask_b32_e32 v102, v202, v102, vcc
	v_cmp_lt_u32_e64 s[98:99], s59, v165
	v_cmp_lt_u32_e64 s[100:101], s59, v164
	v_cmp_lt_u32_e32 vcc, s59, v204
	v_cndmask_b32_e64 v103, v202, v103, s[98:99]
	v_cndmask_b32_e64 v104, v202, v104, s[100:101]
	v_cndmask_b32_e32 v105, v202, v105, vcc
	v_cmp_lt_u32_e64 s[98:99], s59, v252
	v_cmp_lt_u32_e64 s[100:101], s59, v251
	v_cmp_lt_u32_e32 vcc, s59, v250
	v_cndmask_b32_e64 v106, v202, v106, s[98:99]
	v_cndmask_b32_e64 v107, v202, v107, s[100:101]
	v_cndmask_b32_e32 v108, v202, v108, vcc
	v_cmp_lt_u32_e64 s[98:99], s59, v249
	v_cmp_lt_u32_e64 s[100:101], s59, v203
	v_cmp_lt_u32_e32 vcc, s59, v201
	v_cndmask_b32_e64 v109, v202, v109, s[98:99]
	v_cndmask_b32_e64 v110, v202, v110, s[100:101]
	v_cndmask_b32_e32 v111, v202, v111, vcc

; #define LAS __attribute__((address_space(3)))
; __device__ __forceinline__ void stage_v(const KVFrag& f, LAS unsigned char* vst, int lane, int hi, bf16x8 (&vf)[2][2], bf16x8 (&kf)[4]) {
; #pragma unroll
;     for (int i = 0; i < 4; ++i) { const int c = lane + 64 * i; *(LAS bf16x8*)(vst + (c >> 3) * VST_RS + (c & 7) * 16) = f.vr[i]; *(LAS bf16x8*)(vst + KST_OFF + (c >> 3) * KST_RS + (c & 7) * 16) = f.kr[i]; }
;     const LAS unsigned char* tb = vst + (8 * hi + ((lane & 15) >> 2)) * VST_RS + (16 * ((lane >> 4) & 1) + 4 * (lane & 3)) * 2;
; #pragma unroll
;     for (int ks = 0; ks < 2; ++ks)
; #pragma unroll
;         for (int dh = 0; dh < 2; ++dh) {
;             const s16x4 lo = __builtin_bit_cast(s16x4, __builtin_amdgcn_ds_read_tr16_b64_v4i16((LAS s16x4*)(tb + (16 * ks) * VST_RS + dh * 64)));
;             const s16x4 hi4 = __builtin_bit_cast(s16x4, __builtin_amdgcn_ds_read_tr16_b64_v4i16((LAS s16x4*)(tb + (16 * ks + 4) * VST_RS + dh * 64)));
;             vf[ks][dh] = (bf16x8){lo[0], lo[1], lo[2], lo[3], hi4[0], hi4[1], hi4[2], hi4[3]};
;         }
;     const int l31 = lane & 31, jsw = (l31 & 0x13) | ((l31 & 4) << 1) | ((l31 & 8) >> 1);
;     const LAS unsigned char* kb_ = vst + KST_OFF + jsw * KST_RS + 16 * hi;
; #pragma unroll
;     for (int d0 = 0; d0 < 4; ++d0) kf[d0] = *(const LAS bf16x8*)(kb_ + 32 * d0);
; }
; __device__ __forceinline__ unsigned orow_off(const ORows& R, int rr) { return (R.base_row + R.pstride * ((unsigned)rr & R.amask)) * R.ld + R.hcol + 64u * ((unsigned)rr >> R.ashift); }
; __device__ __forceinline__ void qk_tile(const bf16x8 (&kf)[4], const LAS unsigned char* qh, f32x16& s) {
;     const f32x16 z = {0.f, 0.f, 0.f, 0.f, 0.f, 0.f, 0.f, 0.f, 0.f, 0.f, 0.f, 0.f, 0.f, 0.f, 0.f, 0.f};
;     s = __builtin_amdgcn_mfma_f32_32x32x16_bf16(kf[0], *(const LAS bf16x8*)qh, z, 0, 0, 0);
; #pragma unroll
;     for (int d0 = 1; d0 < 4; ++d0) s = __builtin_amdgcn_mfma_f32_32x32x16_bf16(kf[d0], *(const LAS bf16x8*)(qh + 32 * d0), s, 0, 0, 0);
; }
; __device__ __forceinline__ void softmax_head(f32x16& s, int kb, int lq, int radius, bool full, int hi, HState& S) {
;     if (!full) {
; #pragma unroll
;         for (int r = 0; r < 16; ++r) { const int lk = kb + 16 * (r >> 3) + 8 * hi + (r & 7); const int d = lk - lq;
;             const bool valid = (unsigned)(d + radius) <= (unsigned)(2 * radius); s[r] = valid ? s[r] : -INFINITY; }
;     }
.LBB0_517:
	s_add_i32 s46, s6, s43
	s_add_i32 s45, s46, 0xffffff80
	v_ashrrev_i32_e32 v173, 31, v172
	v_lshlrev_b64 v[2:3], 1, v[172:173]
	v_lshl_add_u64 v[14:15], s[18:19], 0, v[2:3]
	v_lshl_add_u64 v[104:105], s[20:21], 0, v[2:3]
	global_load_dwordx4 v[2:5], v[14:15], off
	global_load_dwordx4 v[6:9], v[14:15], off offset:1024
	s_waitcnt vmcnt(7)
	ds_write_b128 v197, v[120:123] offset:9216
	ds_write_b128 v182, v[112:115] offset:15360
	s_waitcnt vmcnt(6)
	ds_write_b128 v198, v[124:127] offset:9216
	ds_write_b128 v183, v[116:119] offset:15360
	s_waitcnt vmcnt(3)
	ds_write_b128 v199, v[136:139] offset:9216
	ds_write_b128 v184, v[128:131] offset:15360
	s_waitcnt vmcnt(2)
	ds_write_b128 v205, v[140:143] offset:9216
	ds_write_b128 v185, v[132:135] offset:15360
	v_add_u32_e32 v0, v186, v187
	ds_read_b128 v[96:99], v207 offset:15360
	global_load_dwordx4 v[112:115], v[104:105], off
	global_load_dwordx4 v[10:13], v[104:105], off offset:1024
	ds_read_b128 v[80:83], v0
	global_load_dwordx4 v[120:123], v[14:15], off offset:2048
	global_load_dwordx4 v[116:119], v[14:15], off offset:3072
	ds_read_b128 v[148:151], v207 offset:15392
	ds_read_b128 v[100:103], v0 offset:32
	global_load_dwordx4 v[128:131], v[104:105], off offset:2048
	global_load_dwordx4 v[124:127], v[104:105], off offset:3072
	s_waitcnt lgkmcnt(2)
	v_mfma_f32_32x32x16_bf16 v[80:95], v[96:99], v[80:83], 0
	s_cmp_ge_i32 s45, s15
	s_cselect_b64 s[34:35], -1, 0
	s_cmp_le_i32 s45, s16
	s_cselect_b64 s[36:37], -1, 0
	s_and_b64 s[36:37], s[34:35], s[36:37]
	v_add_u32_e32 v14, s43, v196
	s_and_b64 vcc, exec, s[36:37]
	s_waitcnt lgkmcnt(0)
	v_mfma_f32_32x32x16_bf16 v[80:95], v[148:151], v[100:103], v[80:95]
	ds_read_b128 v[156:159], v207 offset:15424
	ds_read_b128 v[100:103], v0 offset:64
	ds_read_b128 v[152:155], v207 offset:15456
	ds_read_b128 v[104:107], v0 offset:96
	ds_read_b64_tr_b16 v[132:133], v206 offset:9216
	ds_read_b64_tr_b16 v[134:135], v206 offset:9984
	ds_read_b64_tr_b16 v[138:139], v206 offset:10048
	ds_read_b64_tr_b16 v[136:137], v206 offset:9280
	ds_read_b64_tr_b16 v[140:141], v206 offset:12288
	ds_read_b64_tr_b16 v[142:143], v206 offset:13056
	ds_read_b64_tr_b16 v[146:147], v206 offset:13120
	ds_read_b64_tr_b16 v[144:145], v206 offset:12352
	v_cmp_gt_u32_e64 s[34:35], s72, v14
	v_add_u32_e32 v208, 0xffffff00, v14
	v_add_u32_e32 v204, 0xffffff01, v14
	v_add_u32_e32 v203, 0xffffff02, v14
	v_add_u32_e32 v201, 0xffffff03, v14
	s_waitcnt lgkmcnt(10)
	v_mfma_f32_32x32x16_bf16 v[80:95], v[156:159], v[100:103], v[80:95]
	v_add_u32_e32 v200, 0xffffff04, v14
	v_add_u32_e32 v173, 0xffffff05, v14
	v_add_u32_e32 v167, 0xffffff06, v14
	v_add_u32_e32 v166, 0xffffff0f, v14
	v_add_u32_e32 v165, 0xffffff10, v14
	v_add_u32_e32 v164, 0xffffff11, v14
	v_add_u32_e32 v163, 0xffffff12, v14
	s_waitcnt lgkmcnt(8)
	v_mfma_f32_32x32x16_bf16 v[80:95], v[152:155], v[104:107], v[80:95]
	v_add_u32_e32 v162, 0xffffff13, v14
	v_add_u32_e32 v161, 0xffffff14, v14
	v_add_u32_e32 v160, 0xffffff15, v14
	v_add_u32_e32 v15, 0xffffff16, v14
	s_cbranch_vccnz .LBB0_519
	v_cmp_lt_u32_e32 vcc, s73, v208
	s_nop 5
	v_cndmask_b32_e64 v80, v202, v80, s[34:35]
	v_cndmask_b32_e32 v81, v202, v81, vcc
	v_cmp_lt_u32_e64 s[98:99], s73, v204
	v_cmp_lt_u32_e64 s[100:101], s73, v203
	v_cmp_lt_u32_e32 vcc, s73, v201
	v_cndmask_b32_e64 v82, v202, v82, s[98:99]
	v_cndmask_b32_e64 v83, v202, v83, s[100:101]
	v_cndmask_b32_e32 v84, v202, v84, vcc
	v_cmp_lt_u32_e64 s[98:99], s73, v200
	v_cmp_lt_u32_e64 s[100:101], s73, v173
	v_cmp_lt_u32_e32 vcc, s73, v167
	v_cndmask_b32_e64 v85, v202, v85, s[98:99]
	v_cndmask_b32_e64 v86, v202, v86, s[100:101]
	v_cndmask_b32_e32 v87, v202, v87, vcc
	v_cmp_lt_u32_e64 s[98:99], s73, v166
	v_cmp_lt_u32_e64 s[100:101], s73, v165
	v_cmp_lt_u32_e32 vcc, s73, v164
	v_cndmask_b32_e64 v88, v202, v88, s[98:99]
	v_cndmask_b32_e64 v89, v202, v89, s[100:101]
	v_cndmask_b32_e32 v90, v202, v90, vcc
	v_cmp_lt_u32_e64 s[98:99], s73, v163
	v_cmp_lt_u32_e64 s[100:101], s73, v162
	v_cmp_lt_u32_e32 vcc, s73, v161
	v_cndmask_b32_e64 v91, v202, v91, s[98:99]
	v_cndmask_b32_e64 v92, v202, v92, s[100:101]
	v_cndmask_b32_e32 v93, v202, v93, vcc
	v_cmp_lt_u32_e64 s[98:99], s73, v160
	v_cmp_lt_u32_e32 vcc, s73, v15
	s_nop 0
	v_cndmask_b32_e64 v94, v202, v94, s[98:99]
	v_cndmask_b32_e32 v95, v202, v95, vcc

; #define LAS __attribute__((address_space(3)))
; __device__ __forceinline__ void qk_tile(const bf16x8 (&kf)[4], const LAS unsigned char* qh, f32x16& s) {
;     const f32x16 z = {0.f, 0.f, 0.f, 0.f, 0.f, 0.f, 0.f, 0.f, 0.f, 0.f, 0.f, 0.f, 0.f, 0.f, 0.f, 0.f};
;     s = __builtin_amdgcn_mfma_f32_32x32x16_bf16(kf[0], *(const LAS bf16x8*)qh, z, 0, 0, 0);
; #pragma unroll
;     for (int d0 = 1; d0 < 4; ++d0) s = __builtin_amdgcn_mfma_f32_32x32x16_bf16(kf[d0], *(const LAS bf16x8*)(qh + 32 * d0), s, 0, 0, 0);
; }
; __device__ __forceinline__ void softmax_head(f32x16& s, int kb, int lq, int radius, bool full, int hi, HState& S) {
;     if (!full) {
; #pragma unroll
;         for (int r = 0; r < 16; ++r) { const int lk = kb + 16 * (r >> 3) + 8 * hi + (r & 7); const int d = lk - lq;
;             const bool valid = (unsigned)(d + radius) <= (unsigned)(2 * radius); s[r] = valid ? s[r] : -INFINITY; }
;     }
.LBB0_521:
	s_xor_b64 s[34:35], s[36:37], -1
	ds_read_b128 v[100:103], v0 offset:4608
	ds_read_b128 v[210:213], v0 offset:4640
	s_waitcnt lgkmcnt(1)
	v_mfma_f32_32x32x16_bf16 v[96:111], v[96:99], v[100:103], 0
	s_waitcnt lgkmcnt(0)
	v_mfma_f32_32x32x16_bf16 v[96:111], v[148:151], v[210:213], v[96:111]
	ds_read_b128 v[148:151], v0 offset:4672
	s_waitcnt lgkmcnt(0)
	v_mfma_f32_32x32x16_bf16 v[96:111], v[156:159], v[148:151], v[96:111]
	ds_read_b128 v[148:151], v0 offset:4704
	s_waitcnt lgkmcnt(0)
	v_mfma_f32_32x32x16_bf16 v[96:111], v[152:155], v[148:151], v[96:111]
	s_andn2_b64 vcc, exec, s[34:35]
	s_cbranch_vccnz .LBB0_523
	v_cmp_gt_u32_e32 vcc, s72, v14
	s_nop 8
	v_cndmask_b32_e32 v96, v202, v96, vcc
	v_cmp_lt_u32_e64 s[98:99], s73, v208
	v_cmp_lt_u32_e64 s[100:101], s73, v204
	v_cmp_lt_u32_e32 vcc, s73, v203
	v_cndmask_b32_e64 v97, v202, v97, s[98:99]
	v_cndmask_b32_e64 v98, v202, v98, s[100:101]
	v_cndmask_b32_e32 v99, v202, v99, vcc
	v_cmp_lt_u32_e64 s[98:99], s73, v201
	v_cmp_lt_u32_e64 s[100:101], s73, v200
	v_cmp_lt_u32_e32 vcc, s73, v173
	v_cndmask_b32_e64 v100, v202, v100, s[98:99]
	v_cndmask_b32_e64 v101, v202, v101, s[100:101]
	v_cndmask_b32_e32 v102, v202, v102, vcc
	v_cmp_lt_u32_e64 s[98:99], s73, v167
	v_cmp_lt_u32_e64 s[100:101], s73, v166
	v_cmp_lt_u32_e32 vcc, s73, v165
	v_cndmask_b32_e64 v103, v202, v103, s[98:99]
	v_cndmask_b32_e64 v104, v202, v104, s[100:101]
	v_cndmask_b32_e32 v105, v202, v105, vcc
	v_cmp_lt_u32_e64 s[98:99], s73, v164
	v_cmp_lt_u32_e64 s[100:101], s73, v163
	v_cmp_lt_u32_e32 vcc, s73, v162
	v_cndmask_b32_e64 v106, v202, v106, s[98:99]
	v_cndmask_b32_e64 v107, v202, v107, s[100:101]
	v_cndmask_b32_e32 v108, v202, v108, vcc
	v_cmp_lt_u32_e64 s[98:99], s73, v161
	v_cmp_lt_u32_e64 s[100:101], s73, v160
	v_cmp_lt_u32_e32 vcc, s73, v15
	v_cndmask_b32_e64 v109, v202, v109, s[98:99]
	v_cndmask_b32_e64 v110, v202, v110, s[100:101]
	v_cndmask_b32_e32 v111, v202, v111, vcc

; __device__ __forceinline__ void stage_v(const KVFrag& f, LAS unsigned char* vst, int lane, int hi, bf16x8 (&vf)[2][2], bf16x8 (&kf)[4]) {
; #pragma unroll
;     for (int i = 0; i < 4; ++i) { const int c = lane + 64 * i; *(LAS bf16x8*)(vst + (c >> 3) * VST_RS + (c & 7) * 16) = f.vr[i]; *(LAS bf16x8*)(vst + KST_OFF + (c >> 3) * KST_RS + (c & 7) * 16) = f.kr[i]; }
;     const LAS unsigned char* tb = vst + (8 * hi + ((lane & 15) >> 2)) * VST_RS + (16 * ((lane >> 4) & 1) + 4 * (lane & 3)) * 2;
; #pragma unroll
;     for (int ks = 0; ks < 2; ++ks)
; #pragma unroll
;         for (int dh = 0; dh < 2; ++dh) {
;             const s16x4 lo = __builtin_bit_cast(s16x4, __builtin_amdgcn_ds_read_tr16_b64_v4i16((LAS s16x4*)(tb + (16 * ks) * VST_RS + dh * 64)));
;             const s16x4 hi4 = __builtin_bit_cast(s16x4, __builtin_amdgcn_ds_read_tr16_b64_v4i16((LAS s16x4*)(tb + (16 * ks + 4) * VST_RS + dh * 64)));
;             vf[ks][dh] = (bf16x8){lo[0], lo[1], lo[2], lo[3], hi4[0], hi4[1], hi4[2], hi4[3]};
;         }
;     const int l31 = lane & 31, jsw = (l31 & 0x13) | ((l31 & 4) << 1) | ((l31 & 8) >> 1);
;     const LAS unsigned char* kb_ = vst + KST_OFF + jsw * KST_RS + 16 * hi;
; __device__ __forceinline__ void softmax_tail(f32x16& s, HState& S, u32x4 (&pw)[2]) {
;     const float mn = S.m;
; #pragma unroll
;     for (int r = 0; r < 16; ++r) s[r] -= mn;
; #pragma unroll
;     for (int r = 0; r < 16; ++r) s[r] = __builtin_amdgcn_exp2f(s[r]);
;     float p0 = s[0], p1 = s[1];
; #pragma unroll
;     for (int r = 2; r < 16; r += 2) { p0 += s[r]; p1 += s[r + 1]; }
;     S.l += p0 + p1;
; #pragma unroll
;     for (int ks = 0; ks < 2; ++ks) { pw[ks].x = cvtpk_s(s[8 * ks + 0], s[8 * ks + 1]); pw[ks].y = cvtpk_s(s[8 * ks + 2], s[8 * ks + 3]); pw[ks].z = cvtpk_s(s[8 * ks + 4], s[8 * ks + 5]); pw[ks].w = cvtpk_s(s[8 * ks + 6], s[8 * ks + 7]); }
; }
; __device__ __forceinline__ void softmax_tile(f32x16& s, int kb, int lq, int radius, bool full, int hi, HState& S, u32x4 (&pw)[2]) { softmax_head(s, kb, lq, radius, full, hi, S); softmax_tail(s, S, pw); }
; __device__ __forceinline__ void pv_tile(const bf16x8 (&vf)[2][2], const u32x4 (&pw)[2], HState& S) {
; #pragma unroll
;     for (int ks = 0; ks < 2; ++ks)
; #pragma unroll
;         for (int dh = 0; dh < 2; ++dh) S.o[dh] = __builtin_amdgcn_mfma_f32_32x32x16_bf16(vf[ks][dh], __builtin_bit_cast(bf16x8, pw[ks]), S.o[dh], 0, 0, 0);
.LBB0_525:
	v_sub_f32_e32 v15, v80, v168
	v_sub_f32_e32 v80, v81, v168
	v_sub_f32_e32 v81, v82, v168
	v_sub_f32_e32 v82, v83, v168
	v_sub_f32_e32 v83, v84, v168
	v_sub_f32_e32 v84, v85, v168
	v_sub_f32_e32 v85, v86, v168
	v_sub_f32_e32 v86, v87, v168
	v_sub_f32_e32 v87, v88, v168
	v_sub_f32_e32 v88, v89, v168
	v_sub_f32_e32 v89, v90, v168
	v_sub_f32_e32 v90, v91, v168
	v_sub_f32_e32 v91, v92, v168
	v_sub_f32_e32 v92, v93, v168
	v_sub_f32_e32 v93, v94, v168
	v_sub_f32_e32 v94, v95, v168
	v_exp_f32_e32 v201, v15
	v_exp_f32_e32 v203, v80
	v_exp_f32_e32 v222, v81
	v_exp_f32_e32 v223, v82
	v_exp_f32_e32 v224, v83
	v_exp_f32_e32 v225, v84
	v_exp_f32_e32 v226, v85
	v_exp_f32_e32 v227, v86
	v_exp_f32_e32 v228, v87
	v_exp_f32_e32 v229, v88
	v_exp_f32_e32 v230, v89
	v_exp_f32_e32 v231, v90
	v_exp_f32_e32 v232, v91
	v_exp_f32_e32 v233, v92
	v_exp_f32_e32 v234, v93
	v_exp_f32_e32 v235, v94
	v_cvt_pk_bf16_f32 v80, v228, v229
	v_cvt_pk_bf16_f32 v81, v230, v231
	v_cvt_pk_bf16_f32 v82, v232, v233
	v_cvt_pk_bf16_f32 v83, v234, v235
	v_cvt_pk_bf16_f32 v84, v201, v203
	v_cvt_pk_bf16_f32 v85, v222, v223
	v_cvt_pk_bf16_f32 v86, v224, v225
	v_cvt_pk_bf16_f32 v87, v226, v227
	s_addk_i32 s46, 0xffa0
	s_nop 0
	v_mfma_f32_32x32x16_bf16 v[64:79], v[132:135], v[84:87], v[64:79]
	v_sub_f32_e32 v15, v96, v169
	v_sub_f32_e32 v88, v105, v169
	v_sub_f32_e32 v89, v106, v169
	v_sub_f32_e32 v90, v107, v169
	v_sub_f32_e32 v91, v108, v169
	v_sub_f32_e32 v92, v109, v169
	v_sub_f32_e32 v93, v110, v169
	v_sub_f32_e32 v94, v111, v169
	v_mfma_f32_32x32x16_bf16 v[48:63], v[136:139], v[84:87], v[48:63]
	v_sub_f32_e32 v84, v101, v169
	v_sub_f32_e32 v85, v102, v169
	v_sub_f32_e32 v86, v103, v169
	v_sub_f32_e32 v87, v104, v169
	v_exp_f32_e32 v15, v15
	v_exp_f32_e32 v211, v84
	v_exp_f32_e32 v212, v85
	v_mfma_f32_32x32x16_bf16 v[64:79], v[140:143], v[80:83], v[64:79]
	v_exp_f32_e32 v213, v86
	v_exp_f32_e32 v214, v87
	v_exp_f32_e32 v215, v88
	v_exp_f32_e32 v216, v89
	v_exp_f32_e32 v217, v90
	v_exp_f32_e32 v218, v91
	v_exp_f32_e32 v219, v92
	v_mfma_f32_32x32x16_bf16 v[48:63], v[144:147], v[80:83], v[48:63]
	v_sub_f32_e32 v80, v97, v169
	v_sub_f32_e32 v81, v98, v169
	v_sub_f32_e32 v82, v99, v169
	v_sub_f32_e32 v83, v100, v169
	v_exp_f32_e32 v173, v80
	v_exp_f32_e32 v208, v81
	v_exp_f32_e32 v209, v82
	v_exp_f32_e32 v210, v83
	v_exp_f32_e32 v220, v93
	v_exp_f32_e32 v221, v94
	v_cvt_pk_bf16_f32 v80, v214, v215
	v_cvt_pk_bf16_f32 v81, v216, v217
	v_cvt_pk_bf16_f32 v82, v218, v219
	v_cvt_pk_bf16_f32 v83, v220, v221
	v_cvt_pk_bf16_f32 v84, v15, v173
	v_cvt_pk_bf16_f32 v85, v208, v209
	v_cvt_pk_bf16_f32 v86, v210, v211
	v_cvt_pk_bf16_f32 v87, v212, v213
	s_nop 1
	v_mfma_f32_32x32x16_bf16 v[32:47], v[132:135], v[84:87], v[32:47]
	v_mfma_f32_32x32x16_bf16 v[16:31], v[136:139], v[84:87], v[16:31]
	v_mfma_f32_32x32x16_bf16 v[32:47], v[140:143], v[80:83], v[32:47]
	v_mfma_f32_32x32x16_bf16 v[16:31], v[144:147], v[80:83], v[16:31]
	s_add_i32 s36, s44, 2
	s_min_i32 s34, s36, s14
	v_lshl_add_u32 v80, s34, 11, v195
	v_ashrrev_i32_e32 v81, 31, v80
	v_lshlrev_b64 v[80:81], 1, v[80:81]
	v_lshl_add_u64 v[82:83], s[18:19], 0, v[80:81]
	v_lshl_add_u64 v[100:101], s[20:21], 0, v[80:81]
	s_waitcnt vmcnt(5)
	ds_write_b128 v197, v[112:115] offset:9216
	ds_write_b128 v182, v[2:5] offset:15360
	s_waitcnt vmcnt(4)
	ds_write_b128 v198, v[10:13] offset:9216
	ds_write_b128 v183, v[6:9] offset:15360
	s_waitcnt vmcnt(1)
	ds_write_b128 v199, v[128:131] offset:9216
	ds_write_b128 v184, v[120:123] offset:15360
	s_waitcnt vmcnt(0)
	ds_write_b128 v205, v[124:127] offset:9216
	ds_write_b128 v185, v[116:119] offset:15360
	global_load_dwordx4 v[112:115], v[82:83], off
	global_load_dwordx4 v[116:119], v[82:83], off offset:1024
	global_load_dwordx4 v[120:123], v[100:101], off
	global_load_dwordx4 v[124:127], v[100:101], off offset:1024
	global_load_dwordx4 v[128:131], v[82:83], off offset:2048
	global_load_dwordx4 v[132:135], v[82:83], off offset:3072
	global_load_dwordx4 v[136:139], v[100:101], off offset:2048
	global_load_dwordx4 v[140:143], v[100:101], off offset:3072
	ds_read_b128 v[96:99], v207 offset:15360
	ds_read_b128 v[2:5], v0
	ds_read_b128 v[148:151], v207 offset:15392
	s_waitcnt lgkmcnt(1)
	v_mfma_f32_32x32x16_bf16 v[80:95], v[96:99], v[2:5], 0
	ds_read_b128 v[6:9], v0 offset:32
	ds_read_b128 v[156:159], v207 offset:15424
	ds_read_b128 v[2:5], v0 offset:64
	ds_read_b128 v[152:155], v207 offset:15456
	ds_read_b128 v[100:103], v0 offset:96
	ds_read_b64_tr_b16 v[12:13], v206 offset:10048
	ds_read_b64_tr_b16 v[10:11], v206 offset:9280
	s_waitcnt lgkmcnt(6)
	v_mfma_f32_32x32x16_bf16 v[80:95], v[148:151], v[6:9], v[80:95]
	ds_read_b64_tr_b16 v[6:7], v206 offset:9216
	ds_read_b64_tr_b16 v[8:9], v206 offset:9984
	ds_read_b64_tr_b16 v[144:145], v206 offset:12288
	ds_read_b64_tr_b16 v[146:147], v206 offset:13056
	s_cmp_ge_i32 s46, s15
	s_cselect_b64 s[34:35], -1, 0
	s_cmp_le_i32 s45, s17
	s_waitcnt lgkmcnt(8)
	v_mfma_f32_32x32x16_bf16 v[80:95], v[156:159], v[2:5], v[80:95]
	ds_read_b64_tr_b16 v[4:5], v206 offset:13120
	ds_read_b64_tr_b16 v[2:3], v206 offset:12352
	s_cselect_b64 s[46:47], -1, 0
	s_and_b64 s[34:35], s[34:35], s[46:47]
	s_and_b64 vcc, exec, s[34:35]
	v_add_u32_e32 v163, 32, v14
	v_add_u32_e32 v162, 0xffffff20, v14
	s_waitcnt lgkmcnt(8)
	v_mfma_f32_32x32x16_bf16 v[80:95], v[152:155], v[100:103], v[80:95]
	v_add_u32_e32 v161, 0xffffff21, v14
	v_add_u32_e32 v160, 0xffffff22, v14
	v_add_u32_e32 v167, 0xffffff23, v14
	v_add_u32_e32 v166, 0xffffff24, v14
	v_add_u32_e32 v165, 0xffffff25, v14
	v_add_u32_e32 v164, 0xffffff26, v14
	v_add_u32_e32 v204, 0xffffff2f, v14
	v_add_u32_e32 v242, 0xffffff30, v14
	v_add_u32_e32 v241, 0xffffff31, v14
	v_add_u32_e32 v240, 0xffffff32, v14
	v_add_u32_e32 v239, 0xffffff33, v14
	v_add_u32_e32 v238, 0xffffff34, v14
	v_add_u32_e32 v237, 0xffffff35, v14
	v_add_u32_e32 v236, 0xffffff36, v14
	s_cbranch_vccnz .LBB0_527
; __device__ __forceinline__ void softmax_head(f32x16& s, int kb, int lq, int radius, bool full, int hi, HState& S) {
;     if (!full) {
; #pragma unroll
;         for (int r = 0; r < 16; ++r) { const int lk = kb + 16 * (r >> 3) + 8 * hi + (r & 7); const int d = lk - lq;
;             const bool valid = (unsigned)(d + radius) <= (unsigned)(2 * radius); s[r] = valid ? s[r] : -INFINITY; }
;     }
	v_cmp_gt_u32_e32 vcc, s72, v163
	s_nop 1
	v_cndmask_b32_e32 v80, v202, v80, vcc
	v_cmp_lt_u32_e64 s[98:99], s73, v162
	v_cmp_lt_u32_e64 s[100:101], s73, v161
	v_cmp_lt_u32_e32 vcc, s73, v160
	v_cndmask_b32_e64 v81, v202, v81, s[98:99]
	v_cndmask_b32_e64 v82, v202, v82, s[100:101]
	v_cndmask_b32_e32 v83, v202, v83, vcc
	v_cmp_lt_u32_e64 s[98:99], s73, v167
	v_cmp_lt_u32_e64 s[100:101], s73, v166
	v_cmp_lt_u32_e32 vcc, s73, v165
	v_cndmask_b32_e64 v84, v202, v84, s[98:99]
	v_cndmask_b32_e64 v85, v202, v85, s[100:101]
	v_cndmask_b32_e32 v86, v202, v86, vcc
	v_cmp_lt_u32_e64 s[98:99], s73, v164
	v_cmp_lt_u32_e64 s[100:101], s73, v204
	v_cmp_lt_u32_e32 vcc, s73, v242
	v_cndmask_b32_e64 v87, v202, v87, s[98:99]
	v_cndmask_b32_e64 v88, v202, v88, s[100:101]
	v_cndmask_b32_e32 v89, v202, v89, vcc
	v_cmp_lt_u32_e64 s[98:99], s73, v241
	v_cmp_lt_u32_e64 s[100:101], s73, v240
	v_cmp_lt_u32_e32 vcc, s73, v239
	v_cndmask_b32_e64 v90, v202, v90, s[98:99]
	v_cndmask_b32_e64 v91, v202, v91, s[100:101]
	v_cndmask_b32_e32 v92, v202, v92, vcc
	v_cmp_lt_u32_e64 s[98:99], s73, v238
	v_cmp_lt_u32_e64 s[100:101], s73, v237
	v_cmp_lt_u32_e32 vcc, s73, v236
	v_cndmask_b32_e64 v93, v202, v93, s[98:99]
	v_cndmask_b32_e64 v94, v202, v94, s[100:101]
	v_cndmask_b32_e32 v95, v202, v95, vcc

; #define LAS __attribute__((address_space(3)))
; __device__ __forceinline__ void qk_tile(const bf16x8 (&kf)[4], const LAS unsigned char* qh, f32x16& s) {
;     const f32x16 z = {0.f, 0.f, 0.f, 0.f, 0.f, 0.f, 0.f, 0.f, 0.f, 0.f, 0.f, 0.f, 0.f, 0.f, 0.f, 0.f};
;     s = __builtin_amdgcn_mfma_f32_32x32x16_bf16(kf[0], *(const LAS bf16x8*)qh, z, 0, 0, 0);
; #pragma unroll
;     for (int d0 = 1; d0 < 4; ++d0) s = __builtin_amdgcn_mfma_f32_32x32x16_bf16(kf[d0], *(const LAS bf16x8*)(qh + 32 * d0), s, 0, 0, 0);
; }
; __device__ __forceinline__ void softmax_head(f32x16& s, int kb, int lq, int radius, bool full, int hi, HState& S) {
;     if (!full) {
; #pragma unroll
;         for (int r = 0; r < 16; ++r) { const int lk = kb + 16 * (r >> 3) + 8 * hi + (r & 7); const int d = lk - lq;
;             const bool valid = (unsigned)(d + radius) <= (unsigned)(2 * radius); s[r] = valid ? s[r] : -INFINITY; }
;     }
.LBB0_529:
	s_xor_b64 s[34:35], s[34:35], -1
	ds_read_b128 v[100:103], v0 offset:4608
	ds_read_b128 v[222:225], v0 offset:4640
	s_waitcnt lgkmcnt(1)
	v_mfma_f32_32x32x16_bf16 v[96:111], v[96:99], v[100:103], 0
	s_waitcnt lgkmcnt(0)
	v_mfma_f32_32x32x16_bf16 v[96:111], v[148:151], v[222:225], v[96:111]
	ds_read_b128 v[148:151], v0 offset:4672
	s_waitcnt lgkmcnt(0)
	v_mfma_f32_32x32x16_bf16 v[96:111], v[156:159], v[148:151], v[96:111]
	ds_read_b128 v[148:151], v0 offset:4704
	s_waitcnt lgkmcnt(0)
	v_mfma_f32_32x32x16_bf16 v[96:111], v[152:155], v[148:151], v[96:111]
	s_andn2_b64 vcc, exec, s[34:35]
	s_cbranch_vccnz .LBB0_531
	v_cmp_gt_u32_e32 vcc, s72, v163
	s_nop 8
	v_cndmask_b32_e32 v96, v202, v96, vcc
	v_cmp_lt_u32_e64 s[98:99], s73, v162
	v_cmp_lt_u32_e64 s[100:101], s73, v161
	v_cmp_lt_u32_e32 vcc, s73, v160
	v_cndmask_b32_e64 v97, v202, v97, s[98:99]
	v_cndmask_b32_e64 v98, v202, v98, s[100:101]
	v_cndmask_b32_e32 v99, v202, v99, vcc
	v_cmp_lt_u32_e64 s[98:99], s73, v167
	v_cmp_lt_u32_e64 s[100:101], s73, v166
	v_cmp_lt_u32_e32 vcc, s73, v165
	v_cndmask_b32_e64 v100, v202, v100, s[98:99]
	v_cndmask_b32_e64 v101, v202, v101, s[100:101]
	v_cndmask_b32_e32 v102, v202, v102, vcc
	v_cmp_lt_u32_e64 s[98:99], s73, v164
	v_cmp_lt_u32_e64 s[100:101], s73, v204
	v_cmp_lt_u32_e32 vcc, s73, v242
	v_cndmask_b32_e64 v103, v202, v103, s[98:99]
	v_cndmask_b32_e64 v104, v202, v104, s[100:101]
	v_cndmask_b32_e32 v105, v202, v105, vcc
	v_cmp_lt_u32_e64 s[98:99], s73, v241
	v_cmp_lt_u32_e64 s[100:101], s73, v240
	v_cmp_lt_u32_e32 vcc, s73, v239
	v_cndmask_b32_e64 v106, v202, v106, s[98:99]
	v_cndmask_b32_e64 v107, v202, v107, s[100:101]
	v_cndmask_b32_e32 v108, v202, v108, vcc
	v_cmp_lt_u32_e64 s[98:99], s73, v238
	v_cmp_lt_u32_e64 s[100:101], s73, v237
	v_cmp_lt_u32_e32 vcc, s73, v236
	v_cndmask_b32_e64 v109, v202, v109, s[98:99]
	v_cndmask_b32_e64 v110, v202, v110, s[100:101]
	v_cndmask_b32_e32 v111, v202, v111, vcc
